# MLA tile loop rotated: per-tile barrier between sub-tile blocks 2 and 3, block 3 overlapped with the next tile's first QK^T (no bare MFMA / bare VALU section at tile boundaries); on top of v28
# speedup vs baseline: 1.0053x; 1.0053x over previous
.LBB0_472:
	s_waitcnt vmcnt(0) lgkmcnt(0)
	v_lshlrev_b32_e32 v50, 16, v20
	v_and_b32_e32 v51, 0xffff0000, v20
	v_lshlrev_b32_e32 v52, 16, v16
	v_and_b32_e32 v53, 0xffff0000, v16
	s_lshl_b32 s26, s50, 3
	v_pk_mul_f32 v[54:55], v[28:29], v[52:53]
	v_pk_mul_f32 v[28:29], v[28:29], v[50:51]
	s_ashr_i32 s27, s26, 31
	v_pk_fma_f32 v[54:55], v[24:25], v[50:51], v[54:55] neg_lo:[0,0,1] neg_hi:[0,0,1]
	v_pk_fma_f32 v[24:25], v[24:25], v[52:53], v[28:29]
	v_lshlrev_b32_e32 v16, 16, v17
	v_and_b32_e32 v17, 0xffff0000, v17
	s_add_u32 s28, s6, s26
	v_cvt_pk_bf16_f32 v220, v24, v25
	v_lshlrev_b32_e32 v20, 16, v21
	v_and_b32_e32 v21, 0xffff0000, v21
	v_pk_mul_f32 v[24:25], v[30:31], v[16:17]
	s_addc_u32 s29, s7, s27
	v_pk_fma_f32 v[24:25], v[26:27], v[20:21], v[24:25] neg_lo:[0,0,1] neg_hi:[0,0,1]
	v_pk_mul_f32 v[20:21], v[30:31], v[20:21]
	s_lshl_b64 s[28:29], s[28:29], 10
	v_pk_fma_f32 v[16:17], v[26:27], v[16:17], v[20:21]
	v_lshlrev_b32_e32 v20, 16, v18
	v_and_b32_e32 v21, 0xffff0000, v18
	s_add_u32 s54, s38, s28
	v_cvt_pk_bf16_f32 v217, v24, v25
	v_cvt_pk_bf16_f32 v221, v16, v17
	v_lshlrev_b32_e32 v16, 16, v22
	v_and_b32_e32 v17, 0xffff0000, v22
	v_pk_mul_f32 v[24:25], v[44:45], v[20:21]
	s_addc_u32 s55, s39, s29
	s_lshl_b64 s[28:29], s[20:21], 1
	v_pk_fma_f32 v[24:25], v[36:37], v[16:17], v[24:25] neg_lo:[0,0,1] neg_hi:[0,0,1]
	v_pk_mul_f32 v[16:17], v[44:45], v[16:17]
	s_add_u32 s54, s54, s28
	v_and_b32_e32 v234, 63, v48
	v_pk_fma_f32 v[16:17], v[36:37], v[20:21], v[16:17]
	s_addc_u32 s55, s55, s29
	v_cvt_pk_bf16_f32 v222, v16, v17
	v_lshrrev_b32_e32 v16, 3, v234
	s_add_u32 s54, s54, 0x80
	v_lshlrev_b32_e32 v17, 10, v16
	v_bitop3_b32 v16, v16, v48, 7 bitop3:0x78
	s_addc_u32 s55, s55, 0
	s_lshl_b32 s50, s50, 10
	s_add_i32 s56, 0, 0xc000
	v_lshl_or_b32 v236, v16, 4, v17
	s_add_i32 s57, s50, s56
	s_mov_b32 s58, m0
	s_mov_b32 m0, s57
	s_nop 0
	global_load_lds_dwordx4 v236, s[54:55]
	s_mov_b32 m0, s58
	s_lshl_b32 s54, s51, 3
	s_ashr_i32 s55, s54, 31
	s_add_u32 s54, s6, s54
	s_addc_u32 s55, s7, s55
	s_lshl_b64 s[54:55], s[54:55], 10
	s_add_u32 s54, s38, s54
	s_addc_u32 s55, s39, s55
	s_add_u32 s54, s54, s28
	s_addc_u32 s55, s55, s29
	s_add_u32 s54, s54, 0x80
	v_lshlrev_b32_e32 v16, 4, v48
	s_addc_u32 s55, s55, 0
	s_lshl_b32 s51, s51, 10
	v_and_b32_e32 v16, 0x3f0, v16
	s_add_i32 s56, s51, s56
	s_mov_b32 s57, m0
	s_mov_b32 m0, s56
	s_nop 0
	global_load_lds_dwordx4 v236, s[54:55]
	s_mov_b32 m0, s57
	v_add_u32_e32 v70, 0, v16
	v_lshlrev_b32_e32 v44, 16, v19
	v_and_b32_e32 v45, 0xffff0000, v19
	s_waitcnt vmcnt(0)
	s_barrier
	ds_read_b128 v[50:53], v70
	v_lshlrev_b32_e32 v36, 16, v23
	v_and_b32_e32 v37, 0xffff0000, v23
	v_pk_mul_f32 v[16:17], v[46:47], v[44:45]
	v_cvt_pk_bf16_f32 v216, v54, v55
	v_pk_fma_f32 v[16:17], v[38:39], v[36:37], v[16:17] neg_lo:[0,0,1] neg_hi:[0,0,1]
	v_pk_mul_f32 v[36:37], v[46:47], v[36:37]
	ds_read_b128 v[54:57], v70 offset:1024
	v_pk_fma_f32 v[36:37], v[38:39], v[44:45], v[36:37]
	v_lshlrev_b32_e32 v38, 16, v8
	v_and_b32_e32 v39, 0xffff0000, v8
	v_cvt_pk_bf16_f32 v223, v36, v37
	v_lshlrev_b32_e32 v36, 16, v12
	v_and_b32_e32 v37, 0xffff0000, v12
	v_pk_mul_f32 v[44:45], v[40:41], v[38:39]
	v_lshlrev_b32_e32 v8, 16, v9
	v_pk_fma_f32 v[44:45], v[32:33], v[36:37], v[44:45] neg_lo:[0,0,1] neg_hi:[0,0,1]
	v_pk_mul_f32 v[36:37], v[40:41], v[36:37]
	v_and_b32_e32 v9, 0xffff0000, v9
	v_pk_fma_f32 v[32:33], v[32:33], v[38:39], v[36:37]
	v_lshlrev_b32_e32 v12, 16, v13
	v_cvt_pk_bf16_f32 v228, v32, v33
	v_and_b32_e32 v13, 0xffff0000, v13
	v_pk_mul_f32 v[32:33], v[42:43], v[8:9]
	v_cvt_pk_bf16_f32 v218, v24, v25
	v_pk_fma_f32 v[32:33], v[34:35], v[12:13], v[32:33] neg_lo:[0,0,1] neg_hi:[0,0,1]
	v_pk_mul_f32 v[12:13], v[42:43], v[12:13]
	v_cvt_pk_bf16_f32 v219, v16, v17
	v_pk_fma_f32 v[8:9], v[34:35], v[8:9], v[12:13]
	v_lshlrev_b32_e32 v12, 16, v10
	v_and_b32_e32 v13, 0xffff0000, v10
	s_waitcnt lgkmcnt(1)
	v_mfma_f32_32x32x16_bf16 v[16:31], v[50:53], v[184:187], 0
	v_cvt_pk_bf16_f32 v225, v32, v33
	v_cvt_pk_bf16_f32 v229, v8, v9
	v_lshlrev_b32_e32 v8, 16, v14
	v_and_b32_e32 v9, 0xffff0000, v14
	v_mul_f32_e64 v32, v4, v12
	v_mul_f32_e64 v33, v5, v13
	v_cvt_pk_bf16_f32 v224, v44, v45
	v_pk_fma_f32 v[32:33], v[0:1], v[8:9], v[32:33] neg_lo:[0,0,1] neg_hi:[0,0,1]
	ds_read_b128 v[58:61], v70 offset:2048
	ds_read_b128 v[62:65], v70 offset:3072
	v_cvt_pk_bf16_f32 v226, v32, v33
	v_mfma_f32_32x32x16_bf16 v[32:47], v[50:53], v[200:203], 0
	v_mul_f32_e64 v4, v4, v8
	v_mul_f32_e64 v5, v5, v9
	v_readlane_b32 s68, v254, 32
	v_fma_f32 v0, v0, v12, v4
	v_fma_f32 v1, v1, v13, v5
	v_lshlrev_b32_e32 v4, 16, v11
	v_and_b32_e32 v5, 0xffff0000, v11
	v_cvt_pk_bf16_f32 v230, v0, v1
	v_lshlrev_b32_e32 v0, 16, v15
	s_waitcnt lgkmcnt(2)
	v_mfma_f32_32x32x16_bf16 v[16:31], v[54:57], v[188:191], v[16:31]
	v_and_b32_e32 v1, 0xffff0000, v15
	v_mul_f32_e64 v8, v6, v4
	v_mul_f32_e64 v9, v7, v5
	v_readlane_b32 s69, v254, 33
	v_fma_f32 v8, v2, v0, -v8
	v_fma_f32 v9, v3, v1, -v9
	v_pk_mul_f32 v[0:1], v[6:7], v[0:1]
	v_readlane_b32 s70, v254, 34
	v_pk_fma_f32 v[0:1], v[2:3], v[4:5], v[0:1]
	v_mfma_f32_32x32x16_bf16 v[32:47], v[54:57], v[204:207], v[32:47]
	v_readlane_b32 s71, v254, 35
	v_readlane_b32 s72, v254, 36
	v_readlane_b32 s73, v254, 37
	v_readlane_b32 s74, v254, 38
	v_readlane_b32 s75, v254, 39
	v_readlane_b32 s76, v254, 40
	v_readlane_b32 s77, v254, 41
	v_readlane_b32 s78, v254, 42
	v_readlane_b32 s79, v254, 43
	v_readlane_b32 s80, v254, 44
	v_readlane_b32 s81, v254, 45
	v_readlane_b32 s82, v254, 46
	v_readlane_b32 s83, v254, 47
	s_mov_b32 s68, s69
	v_cvt_pk_bf16_f32 v227, v8, v9
	v_cvt_pk_bf16_f32 v231, v0, v1
	s_mov_b32 s70, s69
	s_mov_b32 s71, s69
	s_mov_b32 s72, s69
	s_mov_b32 s73, s69
	s_mov_b32 s74, s69
	s_mov_b32 s75, s69
	s_mov_b32 s76, s69
	s_mov_b32 s77, s69
	s_mov_b32 s78, s69
	s_mov_b32 s79, s69
	s_mov_b32 s80, s69
	s_mov_b32 s81, s69
	s_mov_b32 s82, s69
	s_mov_b32 s83, s69
	v_mov_b64_e32 v[0:1], s[68:69]
	v_mov_b64_e32 v[2:3], s[70:71]
	v_mov_b64_e32 v[4:5], s[72:73]
	v_mov_b64_e32 v[6:7], s[74:75]
	v_mov_b64_e32 v[8:9], s[76:77]
	v_mov_b64_e32 v[10:11], s[78:79]
	v_mov_b64_e32 v[12:13], s[80:81]
	v_mov_b64_e32 v[14:15], s[82:83]
	s_lshl_b32 s68, s52, 4
	s_lshl_b32 s52, s53, 4
	s_ashr_i32 s56, s68, 31
	s_ashr_i32 s57, s52, 31
	s_lshl_b64 s[54:55], s[12:13], 23
	s_lshl_b64 s[26:27], s[26:27], 10
	s_add_u32 s26, s54, s26
	s_waitcnt lgkmcnt(1)
	v_mfma_f32_32x32x16_bf16 v[16:31], v[58:61], v[192:195], v[16:31]
	s_addc_u32 s27, s55, s27
	s_add_u32 s26, s26, s28
	s_addc_u32 s27, s27, s29
	s_add_u32 s54, s54, 0x1d220000
	s_addc_u32 s55, s55, 0
	s_lshl_b64 s[28:29], s[18:19], 10
	s_add_u32 s28, s54, s28
	v_mfma_f32_32x32x16_bf16 v[32:47], v[58:61], v[208:211], v[32:47]
	s_addc_u32 s29, s55, s29
	ds_read_b128 v[66:69], v70 offset:4096
	s_add_u32 s22, s22, s20
	s_addc_u32 s23, s23, s21
	s_lshl_b64 s[22:23], s[22:23], 1
	s_add_u32 s22, s28, s22
	s_addc_u32 s23, s29, s23
	s_waitcnt lgkmcnt(1)
	v_mfma_f32_32x32x16_bf16 v[16:31], v[62:65], v[196:199], v[16:31]
	s_lshl_b64 s[12:13], s[12:13], 19
	s_add_u32 s28, s12, 0x1f201f80
	s_addc_u32 s29, s13, 0
	s_lshl_b64 s[12:13], s[18:19], 6
	s_add_u32 s18, s28, s12
	ds_read_b128 v[70:73], v70 offset:5120
	s_addc_u32 s19, s29, s13
	v_mfma_f32_32x32x16_bf16 v[32:47], v[62:65], v[212:215], v[32:47]
	s_lshl_b64 s[12:13], s[24:25], 1
	s_add_u32 s18, s18, s12
	s_addc_u32 s19, s19, s13
	s_lshl_b64 s[12:13], s[16:17], 10
	s_add_u32 s24, s54, s12
	s_addc_u32 s25, s55, s13
	s_add_u32 s12, s20, s52
	s_waitcnt lgkmcnt(1)
	v_mfma_f32_32x32x16_bf16 v[16:31], v[66:69], v[216:219], v[16:31]
	s_addc_u32 s13, s21, s57
	s_lshl_b64 s[12:13], s[12:13], 1
	s_add_u32 s24, s24, s12
	s_addc_u32 s25, s25, s13
	s_lshl_b64 s[12:13], s[16:17], 6
	s_mov_b32 s53, s69
	s_add_u32 s16, s28, s12
	v_mfma_f32_32x32x16_bf16 v[32:47], v[66:69], v[224:227], v[32:47]
	s_addc_u32 s17, s29, s13
	s_lshl_b64 s[12:13], s[52:53], 1
	s_add_u32 s16, s16, s12
	s_addc_u32 s17, s17, s13
	s_lshl_b64 s[12:13], s[14:15], 10
	s_add_u32 s52, s54, s12
	s_addc_u32 s53, s55, s13
	s_waitcnt lgkmcnt(0)
	v_mfma_f32_32x32x16_bf16 v[16:31], v[70:73], v[220:223], v[16:31]
	s_add_u32 s12, s20, s68
	s_addc_u32 s13, s21, s56
	s_lshl_b64 s[12:13], s[12:13], 1
	s_add_u32 s20, s52, s12
	s_addc_u32 s21, s53, s13
	s_lshl_b64 s[12:13], s[14:15], 6
	s_add_u32 s14, s28, s12
	v_mfma_f32_32x32x16_bf16 v[32:47], v[70:73], v[228:231], v[32:47]
	s_nop 3
	v_max_f32_e32 v17, v17, v17
	v_max_f32_e32 v16, v16, v16
	v_max_f32_e32 v16, v16, v17
	v_max3_f32 v16, v16, v18, v19
	s_addc_u32 s15, s29, s13
	s_mov_b32 s13, s69
	v_writelane_b32 v254, s12, 32
	s_nop 0
	v_max_f32_e32 v18, v33, v33
	v_max_f32_e32 v19, v32, v32
	v_max_f32_e32 v18, v19, v18
	v_max3_f32 v18, v18, v34, v35
	v_max3_f32 v18, v18, v36, v37
	v_max3_f32 v18, v18, v38, v39
	v_max3_f32 v16, v16, v20, v21
	v_max3_f32 v18, v18, v40, v41
	v_writelane_b32 v254, s13, 33
	v_max3_f32 v16, v16, v22, v23
	v_max3_f32 v18, v18, v42, v43
	v_writelane_b32 v254, s14, 34
	v_max3_f32 v16, v16, v24, v25
	v_max3_f32 v18, v18, v44, v45
	v_writelane_b32 v254, s15, 35
	v_max3_f32 v16, v16, v26, v27
	v_max3_f32 v18, v18, v46, v47
	v_writelane_b32 v254, s16, 36
	v_max3_f32 v16, v16, v28, v29
	v_mov_b32_e32 v19, v18
	v_writelane_b32 v254, s17, 37
	v_max3_f32 v16, v16, v30, v31
	v_permlane32_swap_b32_e32 v18, v19
	v_writelane_b32 v254, s18, 38
	v_mov_b32_e32 v17, v16
	v_max_f32_e32 v19, v19, v19
	v_max_f32_e32 v18, v18, v18
	v_writelane_b32 v254, s19, 39
	v_permlane32_swap_b32_e32 v16, v17
	v_max_f32_e32 v18, v18, v19
	v_writelane_b32 v254, s20, 40
	v_max3_f32 v16, v16, v17, v18
	v_writelane_b32 v254, s21, 41
	v_bfe_u32 v50, v48, 2, 2
	v_xor_b32_e32 v64, 0x80000000, v16
	v_lshlrev_b32_e32 v16, 9, v49
	v_lshlrev_b32_e32 v17, 4, v253
	v_lshlrev_b32_e32 v235, 2, v49
	v_writelane_b32 v254, s22, 42
	v_add3_u32 v237, 0, v16, v17
	v_or_b32_e32 v16, v235, v50
	v_lshlrev_b32_e32 v18, 3, v48
	v_writelane_b32 v254, s23, 43
	v_lshlrev_b32_e32 v17, 7, v16
	v_and_b32_e32 v18, 8, v18
	v_writelane_b32 v254, s24, 44
	v_add3_u32 v238, 0, v17, v18
	v_bfe_u32 v17, v48, 1, 1
	v_lshrrev_b32_e32 v18, 3, v48
	v_writelane_b32 v254, s25, 45
	v_and_or_b32 v17, v18, 2, v17
	v_writelane_b32 v254, s26, 46
	v_bitop3_b32 v18, v235, v17, v50 bitop3:0x36
	v_bitop3_b32 v16, v17, v16, 4 bitop3:0x36
	v_writelane_b32 v254, s27, 47
	s_lshl_b64 s[12:13], s[68:69], 1
	v_lshlrev_b32_e32 v239, 4, v18
	v_lshlrev_b32_e32 v240, 4, v16
	s_add_u32 s14, s14, s12
	v_mov_b32_e32 v232, v233
	v_mov_b64_e32 v[30:31], v[14:15]
	v_mov_b64_e32 v[46:47], v[14:15]
	v_mov_b64_e32 v[62:63], v[14:15]
	v_mov_b32_e32 v65, v64
	v_mov_b32_e32 v66, v64
	v_mov_b32_e32 v67, v64
	v_mov_b32_e32 v68, v64
	v_mov_b32_e32 v69, v64
	v_mov_b32_e32 v70, v64
	v_mov_b32_e32 v71, v64
	v_mov_b32_e32 v72, v64
	v_mov_b32_e32 v73, v64
	v_mov_b32_e32 v74, v64
	v_mov_b32_e32 v75, v64
	v_mov_b32_e32 v76, v64
	v_mov_b32_e32 v77, v64
	v_mov_b32_e32 v78, v64
	v_mov_b32_e32 v79, v64
	s_addc_u32 s15, s15, s13
	s_mov_b32 s29, 0
	v_mov_b64_e32 v[28:29], v[12:13]
	v_mov_b64_e32 v[26:27], v[10:11]
	v_mov_b64_e32 v[24:25], v[8:9]
	v_mov_b64_e32 v[22:23], v[6:7]
	v_mov_b64_e32 v[20:21], v[4:5]
	v_mov_b64_e32 v[18:19], v[2:3]
	v_mov_b64_e32 v[16:17], v[0:1]
	v_mov_b64_e32 v[44:45], v[12:13]
	v_mov_b64_e32 v[42:43], v[10:11]
	v_mov_b64_e32 v[40:41], v[8:9]
	v_mov_b64_e32 v[38:39], v[6:7]
	v_mov_b64_e32 v[36:37], v[4:5]
	v_mov_b64_e32 v[34:35], v[2:3]
	v_mov_b64_e32 v[32:33], v[0:1]
	v_mov_b64_e32 v[60:61], v[12:13]
	v_mov_b64_e32 v[58:59], v[10:11]
	v_mov_b64_e32 v[56:57], v[8:9]
	v_mov_b64_e32 v[54:55], v[6:7]
	v_mov_b64_e32 v[52:53], v[4:5]
	v_mov_b64_e32 v[50:51], v[2:3]
	v_mov_b64_e32 v[48:49], v[0:1]
	v_mov_b64_e32 v[244:245], v[232:233]
	s_mov_b64 s[82:83], 0x800
	s_movk_i32 s76, 0xfc00
	s_movk_i32 s78, 0x400
	s_movk_i32 s79, 0x180
	s_movk_i32 s80, 0x200
	v_readlane_b32 s77, v255, 0
	s_and_b32 s12, s29, 1
	s_mul_i32 s13, s12, 0x6000
	v_add_u32_e32 v242, s13, v237
	v_lshl_add_u32 v241, s12, 14, v238
	v_add_u32_e32 v232, v241, v240
	v_add_u32_e32 v241, v241, v239
	ds_read_b128 v[144:147], v242
	ds_read_b128 v[148:151], v242 offset:1024
	ds_read_b128 v[152:155], v242 offset:2048
	ds_read_b128 v[156:159], v242 offset:3072
	ds_read_b128 v[160:163], v242 offset:4096
	ds_read_b128 v[164:167], v242 offset:5120
	s_waitcnt lgkmcnt(5)
	v_mfma_f32_32x32x16_bf16 v[80:95], v[144:147], v[184:187], v[64:79]
	v_mfma_f32_32x32x16_bf16 v[96:111], v[144:147], v[200:203], v[64:79]
	ds_read_b128 v[144:147], v242 offset:6144
	s_waitcnt lgkmcnt(5)
	v_mfma_f32_32x32x16_bf16 v[80:95], v[148:151], v[188:191], v[80:95]
	v_mfma_f32_32x32x16_bf16 v[96:111], v[148:151], v[204:207], v[96:111]
	ds_read_b128 v[148:151], v242 offset:7168
	s_waitcnt lgkmcnt(5)
	v_mfma_f32_32x32x16_bf16 v[80:95], v[152:155], v[192:195], v[80:95]
	v_mfma_f32_32x32x16_bf16 v[96:111], v[152:155], v[208:211], v[96:111]
	ds_read_b128 v[152:155], v242 offset:8192
	s_waitcnt lgkmcnt(5)
	v_mfma_f32_32x32x16_bf16 v[80:95], v[156:159], v[196:199], v[80:95]
	v_mfma_f32_32x32x16_bf16 v[96:111], v[156:159], v[212:215], v[96:111]
	ds_read_b128 v[156:159], v242 offset:9216
	s_waitcnt lgkmcnt(5)
	v_mfma_f32_32x32x16_bf16 v[80:95], v[160:163], v[216:219], v[80:95]
	v_mfma_f32_32x32x16_bf16 v[96:111], v[160:163], v[224:227], v[96:111]
	ds_read_b128 v[160:163], v242 offset:10240
	s_waitcnt lgkmcnt(5)
	v_mfma_f32_32x32x16_bf16 v[80:95], v[164:167], v[220:223], v[80:95]
	v_mfma_f32_32x32x16_bf16 v[96:111], v[164:167], v[228:231], v[96:111]
	ds_read_b128 v[164:167], v242 offset:11264
	ds_read_b64_tr_b16 v[168:169], v241 offset:49152
	ds_read_b64_tr_b16 v[170:171], v241 offset:50176
	ds_read_b64_tr_b16 v[176:177], v232 offset:49152
	ds_read_b64_tr_b16 v[178:179], v232 offset:50176
	ds_read_b64_tr_b16 v[172:173], v241 offset:51200
	ds_read_b64_tr_b16 v[174:175], v241 offset:52224
	ds_read_b64_tr_b16 v[180:181], v232 offset:51200
	ds_read_b64_tr_b16 v[182:183], v232 offset:52224
	s_add_i32 s28, s29, 1
	s_cmp_eq_u32 s29, 63
	s_cbranch_scc1 .LBB0_481

.LBB0_481:
	s_and_b32 s12, s29, 1
	s_mul_i32 s13, s12, 0x6000
	v_add_u32_e32 v242, s13, v237
	v_lshl_add_u32 v241, s12, 14, v238
	v_add_u32_e32 v232, v241, v240
	v_add_u32_e32 v241, v241, v239
	s_waitcnt lgkmcnt(13)
	v_mfma_f32_32x32x16_bf16 v[112:127], v[144:147], v[184:187], v[64:79]
	v_exp_f32_e32 v80, v80
	v_exp_f32_e32 v81, v81
	v_add_f32_e32 v244, v244, v80
	v_add_f32_e32 v244, v244, v81
	v_cvt_pk_bf16_f32 v80, v80, v81
	v_mfma_f32_32x32x16_bf16 v[128:143], v[144:147], v[200:203], v[64:79]
	ds_read_b128 v[144:147], v242 offset:12288
	v_exp_f32_e32 v82, v82
	v_exp_f32_e32 v83, v83
	v_add_f32_e32 v244, v244, v82
	v_add_f32_e32 v244, v244, v83
	v_cvt_pk_bf16_f32 v81, v82, v83
	s_waitcnt lgkmcnt(13)
	v_mfma_f32_32x32x16_bf16 v[112:127], v[148:151], v[188:191], v[112:127]
	v_exp_f32_e32 v84, v84
	v_exp_f32_e32 v85, v85
	v_add_f32_e32 v244, v244, v84
	v_add_f32_e32 v244, v244, v85
	v_cvt_pk_bf16_f32 v82, v84, v85
	v_mfma_f32_32x32x16_bf16 v[128:143], v[148:151], v[204:207], v[128:143]
	ds_read_b128 v[148:151], v242 offset:13312
	v_exp_f32_e32 v86, v86
	v_exp_f32_e32 v87, v87
	v_add_f32_e32 v244, v244, v86
	v_add_f32_e32 v244, v244, v87
	s_waitcnt lgkmcnt(13)
	v_mfma_f32_32x32x16_bf16 v[112:127], v[152:155], v[192:195], v[112:127]
	v_cvt_pk_bf16_f32 v83, v86, v87
	v_exp_f32_e32 v96, v96
	v_exp_f32_e32 v97, v97
	v_add_f32_e32 v245, v245, v96
	v_mfma_f32_32x32x16_bf16 v[128:143], v[152:155], v[208:211], v[128:143]
	ds_read_b128 v[152:155], v242 offset:14336
	v_add_f32_e32 v245, v245, v97
	v_cvt_pk_bf16_f32 v96, v96, v97
	v_exp_f32_e32 v98, v98
	v_exp_f32_e32 v99, v99
	s_waitcnt lgkmcnt(9)
	v_mfma_f32_32x32x16_bf16 v[48:63], v[80:83], v[168:171], v[48:63]
	v_add_f32_e32 v245, v245, v98
	v_add_f32_e32 v245, v245, v99
	v_cvt_pk_bf16_f32 v97, v98, v99
	v_exp_f32_e32 v100, v100
	v_exp_f32_e32 v101, v101
	v_mfma_f32_32x32x16_bf16 v[112:127], v[156:159], v[196:199], v[112:127]
	v_add_f32_e32 v245, v245, v100
	v_add_f32_e32 v245, v245, v101
	v_cvt_pk_bf16_f32 v98, v100, v101
	v_exp_f32_e32 v102, v102
	v_exp_f32_e32 v103, v103
	s_waitcnt lgkmcnt(7)
	v_mfma_f32_32x32x16_bf16 v[32:47], v[80:83], v[176:179], v[32:47]
	v_add_f32_e32 v245, v245, v102
	v_add_f32_e32 v245, v245, v103
	v_cvt_pk_bf16_f32 v99, v102, v103
	v_exp_f32_e32 v88, v88
	v_mfma_f32_32x32x16_bf16 v[128:143], v[156:159], v[212:215], v[128:143]
	ds_read_b128 v[156:159], v242 offset:15360
	v_exp_f32_e32 v89, v89
	v_add_f32_e32 v244, v244, v88
	v_add_f32_e32 v244, v244, v89
	v_cvt_pk_bf16_f32 v88, v88, v89
	v_mfma_f32_32x32x16_bf16 v[112:127], v[160:163], v[216:219], v[112:127]
	v_exp_f32_e32 v90, v90
	v_exp_f32_e32 v91, v91
	v_add_f32_e32 v244, v244, v90
	v_add_f32_e32 v244, v244, v91
	v_cvt_pk_bf16_f32 v89, v90, v91
	v_mfma_f32_32x32x16_bf16 v[128:143], v[160:163], v[224:227], v[128:143]
	ds_read_b128 v[160:163], v242 offset:16384
	v_exp_f32_e32 v92, v92
	v_exp_f32_e32 v93, v93
	v_add_f32_e32 v244, v244, v92
	v_add_f32_e32 v244, v244, v93
	v_cvt_pk_bf16_f32 v90, v92, v93
	v_mfma_f32_32x32x16_bf16 v[16:31], v[96:99], v[168:171], v[16:31]
	v_exp_f32_e32 v94, v94
	v_exp_f32_e32 v95, v95
	v_add_f32_e32 v244, v244, v94
	v_add_f32_e32 v244, v244, v95
	v_mfma_f32_32x32x16_bf16 v[112:127], v[164:167], v[220:223], v[112:127]
	v_cvt_pk_bf16_f32 v91, v94, v95
	v_exp_f32_e32 v104, v104
	v_exp_f32_e32 v105, v105
	v_add_f32_e32 v245, v245, v104
	v_mfma_f32_32x32x16_bf16 v[0:15], v[96:99], v[176:179], v[0:15]
	v_add_f32_e32 v245, v245, v105
	v_cvt_pk_bf16_f32 v104, v104, v105
	v_exp_f32_e32 v106, v106
	v_exp_f32_e32 v107, v107
	v_add_f32_e32 v245, v245, v106
	v_mfma_f32_32x32x16_bf16 v[128:143], v[164:167], v[228:231], v[128:143]
	ds_read_b128 v[164:167], v242 offset:17408
	v_add_f32_e32 v245, v245, v107
	v_cvt_pk_bf16_f32 v105, v106, v107
	v_exp_f32_e32 v108, v108
	v_exp_f32_e32 v109, v109
	v_add_f32_e32 v245, v245, v108
	s_waitcnt lgkmcnt(8)
	v_mfma_f32_32x32x16_bf16 v[48:63], v[88:91], v[172:175], v[48:63]
	v_add_f32_e32 v245, v245, v109
	v_cvt_pk_bf16_f32 v106, v108, v109
	v_exp_f32_e32 v110, v110
	v_exp_f32_e32 v111, v111
	s_waitcnt lgkmcnt(6)
	v_mfma_f32_32x32x16_bf16 v[32:47], v[88:91], v[180:183], v[32:47]
	v_add_f32_e32 v245, v245, v110
	v_add_f32_e32 v245, v245, v111
	v_cvt_pk_bf16_f32 v107, v110, v111
	ds_read_b64_tr_b16 v[168:169], v241 offset:53248
	ds_read_b64_tr_b16 v[170:171], v241 offset:54272
	ds_read_b64_tr_b16 v[176:177], v232 offset:53248
	ds_read_b64_tr_b16 v[178:179], v232 offset:54272
	v_mfma_f32_32x32x16_bf16 v[16:31], v[104:107], v[172:175], v[16:31]
	ds_read_b64_tr_b16 v[172:173], v241 offset:55296
	ds_read_b64_tr_b16 v[174:175], v241 offset:56320
	v_mfma_f32_32x32x16_bf16 v[0:15], v[104:107], v[180:183], v[0:15]
	ds_read_b64_tr_b16 v[180:181], v232 offset:55296
	ds_read_b64_tr_b16 v[182:183], v232 offset:56320
	s_waitcnt lgkmcnt(13)
	v_mfma_f32_32x32x16_bf16 v[80:95], v[144:147], v[184:187], v[64:79]
	v_exp_f32_e32 v112, v112
	v_exp_f32_e32 v113, v113
	v_add_f32_e32 v244, v244, v112
	v_add_f32_e32 v244, v244, v113
	v_cvt_pk_bf16_f32 v112, v112, v113
	v_mfma_f32_32x32x16_bf16 v[96:111], v[144:147], v[200:203], v[64:79]
	ds_read_b128 v[144:147], v242 offset:18432
	v_exp_f32_e32 v114, v114
	v_exp_f32_e32 v115, v115
	v_add_f32_e32 v244, v244, v114
	v_add_f32_e32 v244, v244, v115
	v_cvt_pk_bf16_f32 v113, v114, v115
	s_waitcnt lgkmcnt(13)
	v_mfma_f32_32x32x16_bf16 v[80:95], v[148:151], v[188:191], v[80:95]
	v_exp_f32_e32 v116, v116
	v_exp_f32_e32 v117, v117
	v_add_f32_e32 v244, v244, v116
	v_add_f32_e32 v244, v244, v117
	v_cvt_pk_bf16_f32 v114, v116, v117
	v_mfma_f32_32x32x16_bf16 v[96:111], v[148:151], v[204:207], v[96:111]
	ds_read_b128 v[148:151], v242 offset:19456
	v_exp_f32_e32 v118, v118
	v_exp_f32_e32 v119, v119
	v_add_f32_e32 v244, v244, v118
	v_add_f32_e32 v244, v244, v119
	s_waitcnt lgkmcnt(13)
	v_mfma_f32_32x32x16_bf16 v[80:95], v[152:155], v[192:195], v[80:95]
	v_cvt_pk_bf16_f32 v115, v118, v119
	v_exp_f32_e32 v128, v128
	v_exp_f32_e32 v129, v129
	v_add_f32_e32 v245, v245, v128
	v_mfma_f32_32x32x16_bf16 v[96:111], v[152:155], v[208:211], v[96:111]
	ds_read_b128 v[152:155], v242 offset:20480
	v_add_f32_e32 v245, v245, v129
	v_cvt_pk_bf16_f32 v128, v128, v129
	v_exp_f32_e32 v130, v130
	v_exp_f32_e32 v131, v131
	s_waitcnt lgkmcnt(9)
	v_mfma_f32_32x32x16_bf16 v[48:63], v[112:115], v[168:171], v[48:63]
	v_add_f32_e32 v245, v245, v130
	v_add_f32_e32 v245, v245, v131
	v_cvt_pk_bf16_f32 v129, v130, v131
	v_exp_f32_e32 v132, v132
	v_exp_f32_e32 v133, v133
	v_mfma_f32_32x32x16_bf16 v[80:95], v[156:159], v[196:199], v[80:95]
	v_add_f32_e32 v245, v245, v132
	v_add_f32_e32 v245, v245, v133
	v_cvt_pk_bf16_f32 v130, v132, v133
	v_exp_f32_e32 v134, v134
	v_exp_f32_e32 v135, v135
	s_waitcnt lgkmcnt(7)
	v_mfma_f32_32x32x16_bf16 v[32:47], v[112:115], v[176:179], v[32:47]
	v_add_f32_e32 v245, v245, v134
	v_add_f32_e32 v245, v245, v135
	v_cvt_pk_bf16_f32 v131, v134, v135
	v_exp_f32_e32 v120, v120
	v_mfma_f32_32x32x16_bf16 v[96:111], v[156:159], v[212:215], v[96:111]
	ds_read_b128 v[156:159], v242 offset:21504
	v_exp_f32_e32 v121, v121
	v_add_f32_e32 v244, v244, v120
	v_add_f32_e32 v244, v244, v121
	v_cvt_pk_bf16_f32 v120, v120, v121
	v_mfma_f32_32x32x16_bf16 v[80:95], v[160:163], v[216:219], v[80:95]
	v_exp_f32_e32 v122, v122
	v_exp_f32_e32 v123, v123
	v_add_f32_e32 v244, v244, v122
	v_add_f32_e32 v244, v244, v123
	v_cvt_pk_bf16_f32 v121, v122, v123
	v_mfma_f32_32x32x16_bf16 v[96:111], v[160:163], v[224:227], v[96:111]
	ds_read_b128 v[160:163], v242 offset:22528
	v_exp_f32_e32 v124, v124
	v_exp_f32_e32 v125, v125
	v_add_f32_e32 v244, v244, v124
	v_add_f32_e32 v244, v244, v125
	v_cvt_pk_bf16_f32 v122, v124, v125
	v_mfma_f32_32x32x16_bf16 v[16:31], v[128:131], v[168:171], v[16:31]
	v_exp_f32_e32 v126, v126
	v_exp_f32_e32 v127, v127
	v_add_f32_e32 v244, v244, v126
	v_add_f32_e32 v244, v244, v127
	v_mfma_f32_32x32x16_bf16 v[80:95], v[164:167], v[220:223], v[80:95]
	v_cvt_pk_bf16_f32 v123, v126, v127
	v_exp_f32_e32 v136, v136
	v_exp_f32_e32 v137, v137
	v_add_f32_e32 v245, v245, v136
	v_mfma_f32_32x32x16_bf16 v[0:15], v[128:131], v[176:179], v[0:15]
	v_add_f32_e32 v245, v245, v137
	v_cvt_pk_bf16_f32 v136, v136, v137
	v_exp_f32_e32 v138, v138
	v_exp_f32_e32 v139, v139
	v_add_f32_e32 v245, v245, v138
	v_mfma_f32_32x32x16_bf16 v[96:111], v[164:167], v[228:231], v[96:111]
	ds_read_b128 v[164:167], v242 offset:23552
	v_add_f32_e32 v245, v245, v139
	v_cvt_pk_bf16_f32 v137, v138, v139
	v_exp_f32_e32 v140, v140
	v_exp_f32_e32 v141, v141
	v_add_f32_e32 v245, v245, v140
	s_waitcnt lgkmcnt(8)
	v_mfma_f32_32x32x16_bf16 v[48:63], v[120:123], v[172:175], v[48:63]
	v_add_f32_e32 v245, v245, v141
	v_cvt_pk_bf16_f32 v138, v140, v141
	v_exp_f32_e32 v142, v142
	v_exp_f32_e32 v143, v143
	s_waitcnt lgkmcnt(6)
	v_mfma_f32_32x32x16_bf16 v[32:47], v[120:123], v[180:183], v[32:47]
	v_add_f32_e32 v245, v245, v142
	v_add_f32_e32 v245, v245, v143
	v_cvt_pk_bf16_f32 v139, v142, v143
	ds_read_b64_tr_b16 v[168:169], v241 offset:57344
	ds_read_b64_tr_b16 v[170:171], v241 offset:58368
	ds_read_b64_tr_b16 v[176:177], v232 offset:57344
	ds_read_b64_tr_b16 v[178:179], v232 offset:58368
	v_mfma_f32_32x32x16_bf16 v[16:31], v[136:139], v[172:175], v[16:31]
	ds_read_b64_tr_b16 v[172:173], v241 offset:59392
	ds_read_b64_tr_b16 v[174:175], v241 offset:60416
	v_mfma_f32_32x32x16_bf16 v[0:15], v[136:139], v[180:183], v[0:15]
	ds_read_b64_tr_b16 v[180:181], v232 offset:59392
	ds_read_b64_tr_b16 v[182:183], v232 offset:60416
	s_waitcnt lgkmcnt(13)
	v_mfma_f32_32x32x16_bf16 v[112:127], v[144:147], v[184:187], v[64:79]
	v_exp_f32_e32 v80, v80
	v_exp_f32_e32 v81, v81
	v_add_f32_e32 v244, v244, v80
	v_add_f32_e32 v244, v244, v81
	v_cvt_pk_bf16_f32 v80, v80, v81
	v_mfma_f32_32x32x16_bf16 v[128:143], v[144:147], v[200:203], v[64:79]
	v_exp_f32_e32 v82, v82
	v_exp_f32_e32 v83, v83
	v_add_f32_e32 v244, v244, v82
	v_add_f32_e32 v244, v244, v83
	v_cvt_pk_bf16_f32 v81, v82, v83
	s_waitcnt lgkmcnt(12)
	v_mfma_f32_32x32x16_bf16 v[112:127], v[148:151], v[188:191], v[112:127]
	v_exp_f32_e32 v84, v84
	v_exp_f32_e32 v85, v85
	v_add_f32_e32 v244, v244, v84
	v_add_f32_e32 v244, v244, v85
	v_cvt_pk_bf16_f32 v82, v84, v85
	v_mfma_f32_32x32x16_bf16 v[128:143], v[148:151], v[204:207], v[128:143]
	v_exp_f32_e32 v86, v86
	v_exp_f32_e32 v87, v87
	v_add_f32_e32 v244, v244, v86
	v_add_f32_e32 v244, v244, v87
	s_waitcnt lgkmcnt(11)
	v_mfma_f32_32x32x16_bf16 v[112:127], v[152:155], v[192:195], v[112:127]
	v_cvt_pk_bf16_f32 v83, v86, v87
	v_exp_f32_e32 v96, v96
	v_exp_f32_e32 v97, v97
	v_add_f32_e32 v245, v245, v96
	v_mfma_f32_32x32x16_bf16 v[128:143], v[152:155], v[208:211], v[128:143]
	v_add_f32_e32 v245, v245, v97
	v_cvt_pk_bf16_f32 v96, v96, v97
	v_exp_f32_e32 v98, v98
	v_exp_f32_e32 v99, v99
	s_waitcnt lgkmcnt(6)
	v_mfma_f32_32x32x16_bf16 v[48:63], v[80:83], v[168:171], v[48:63]
	v_add_f32_e32 v245, v245, v98
	v_add_f32_e32 v245, v245, v99
	v_cvt_pk_bf16_f32 v97, v98, v99
	v_exp_f32_e32 v100, v100
	v_exp_f32_e32 v101, v101
	v_mfma_f32_32x32x16_bf16 v[112:127], v[156:159], v[196:199], v[112:127]
	v_add_f32_e32 v245, v245, v100
	v_add_f32_e32 v245, v245, v101
	v_cvt_pk_bf16_f32 v98, v100, v101
	v_exp_f32_e32 v102, v102
	v_exp_f32_e32 v103, v103
	s_waitcnt lgkmcnt(4)
	v_mfma_f32_32x32x16_bf16 v[32:47], v[80:83], v[176:179], v[32:47]
	v_add_f32_e32 v245, v245, v102
	v_add_f32_e32 v245, v245, v103
	v_cvt_pk_bf16_f32 v99, v102, v103
	v_exp_f32_e32 v88, v88
	v_mfma_f32_32x32x16_bf16 v[128:143], v[156:159], v[212:215], v[128:143]
	v_exp_f32_e32 v89, v89
	v_add_f32_e32 v244, v244, v88
	v_add_f32_e32 v244, v244, v89
	v_cvt_pk_bf16_f32 v88, v88, v89
	v_mfma_f32_32x32x16_bf16 v[112:127], v[160:163], v[216:219], v[112:127]
	v_exp_f32_e32 v90, v90
	v_exp_f32_e32 v91, v91
	v_add_f32_e32 v244, v244, v90
	v_add_f32_e32 v244, v244, v91
	v_cvt_pk_bf16_f32 v89, v90, v91
	v_mfma_f32_32x32x16_bf16 v[128:143], v[160:163], v[224:227], v[128:143]
	v_exp_f32_e32 v92, v92
	v_exp_f32_e32 v93, v93
	v_add_f32_e32 v244, v244, v92
	v_add_f32_e32 v244, v244, v93
	v_cvt_pk_bf16_f32 v90, v92, v93
	v_mfma_f32_32x32x16_bf16 v[16:31], v[96:99], v[168:171], v[16:31]
	v_exp_f32_e32 v94, v94
	v_exp_f32_e32 v95, v95
	v_add_f32_e32 v244, v244, v94
	v_add_f32_e32 v244, v244, v95
	v_mfma_f32_32x32x16_bf16 v[112:127], v[164:167], v[220:223], v[112:127]
	v_cvt_pk_bf16_f32 v91, v94, v95
	v_exp_f32_e32 v104, v104
	v_exp_f32_e32 v105, v105
	v_add_f32_e32 v245, v245, v104
	v_mfma_f32_32x32x16_bf16 v[0:15], v[96:99], v[176:179], v[0:15]
	v_add_f32_e32 v245, v245, v105
	v_cvt_pk_bf16_f32 v104, v104, v105
	v_exp_f32_e32 v106, v106
	v_exp_f32_e32 v107, v107
	v_add_f32_e32 v245, v245, v106
	v_mfma_f32_32x32x16_bf16 v[128:143], v[164:167], v[228:231], v[128:143]
	v_add_f32_e32 v245, v245, v107
	v_cvt_pk_bf16_f32 v105, v106, v107
	v_exp_f32_e32 v108, v108
	v_exp_f32_e32 v109, v109
	v_add_f32_e32 v245, v245, v108
	s_waitcnt lgkmcnt(2)
	v_mfma_f32_32x32x16_bf16 v[48:63], v[88:91], v[172:175], v[48:63]
	v_add_f32_e32 v245, v245, v109
	v_cvt_pk_bf16_f32 v106, v108, v109
	v_exp_f32_e32 v110, v110
	v_exp_f32_e32 v111, v111
	s_waitcnt lgkmcnt(0)
	v_mfma_f32_32x32x16_bf16 v[32:47], v[88:91], v[180:183], v[32:47]
	v_add_f32_e32 v245, v245, v110
	v_add_f32_e32 v245, v245, v111
	v_cvt_pk_bf16_f32 v107, v110, v111
	ds_read_b64_tr_b16 v[168:169], v241 offset:61440
	ds_read_b64_tr_b16 v[170:171], v241 offset:62464
	ds_read_b64_tr_b16 v[176:177], v232 offset:61440
	ds_read_b64_tr_b16 v[178:179], v232 offset:62464
	v_mfma_f32_32x32x16_bf16 v[16:31], v[104:107], v[172:175], v[16:31]
	ds_read_b64_tr_b16 v[172:173], v241 offset:63488
	ds_read_b64_tr_b16 v[174:175], v241 offset:64512
	v_mfma_f32_32x32x16_bf16 v[0:15], v[104:107], v[180:183], v[0:15]
	ds_read_b64_tr_b16 v[180:181], v232 offset:63488
	ds_read_b64_tr_b16 v[182:183], v232 offset:64512
	s_waitcnt vmcnt(0)
	s_waitcnt lgkmcnt(0)
	s_barrier
	s_cmp_eq_u32 s28, 64
	s_cbranch_scc1 .Lmla_last
	s_and_b32 s12, s28, 1
	s_mul_i32 s13, s12, 0x6000
	v_add_u32_e32 v242, s13, v237
	v_lshl_add_u32 v241, s12, 14, v238
	v_add_u32_e32 v232, v241, v240
	v_add_u32_e32 v241, v241, v239
	ds_read_b128 v[144:147], v242
	ds_read_b128 v[148:151], v242 offset:1024
	ds_read_b128 v[152:155], v242 offset:2048
	ds_read_b128 v[156:159], v242 offset:3072
	ds_read_b128 v[160:163], v242 offset:4096
	ds_read_b128 v[164:167], v242 offset:5120
	v_exp_f32_e32 v112, v112
	v_exp_f32_e32 v113, v113
	v_add_f32_e32 v244, v244, v112
	v_add_f32_e32 v244, v244, v113
	v_cvt_pk_bf16_f32 v112, v112, v113
	v_exp_f32_e32 v114, v114
	v_exp_f32_e32 v115, v115
	v_add_f32_e32 v244, v244, v114
	v_add_f32_e32 v244, v244, v115
	v_cvt_pk_bf16_f32 v113, v114, v115
	s_waitcnt lgkmcnt(5)
	v_mfma_f32_32x32x16_bf16 v[80:95], v[144:147], v[184:187], v[64:79]
	v_exp_f32_e32 v116, v116
	v_exp_f32_e32 v117, v117
	v_add_f32_e32 v244, v244, v116
	v_add_f32_e32 v244, v244, v117
	v_mfma_f32_32x32x16_bf16 v[96:111], v[144:147], v[200:203], v[64:79]
	ds_read_b128 v[144:147], v242 offset:6144
	v_cvt_pk_bf16_f32 v114, v116, v117
	v_exp_f32_e32 v118, v118
	v_exp_f32_e32 v119, v119
	v_add_f32_e32 v244, v244, v118
	s_waitcnt lgkmcnt(5)
	v_mfma_f32_32x32x16_bf16 v[80:95], v[148:151], v[188:191], v[80:95]
	v_add_f32_e32 v244, v244, v119
	v_cvt_pk_bf16_f32 v115, v118, v119
	v_exp_f32_e32 v128, v128
	v_exp_f32_e32 v129, v129
	v_mfma_f32_32x32x16_bf16 v[96:111], v[148:151], v[204:207], v[96:111]
	ds_read_b128 v[148:151], v242 offset:7168
	v_add_f32_e32 v245, v245, v128
	v_add_f32_e32 v245, v245, v129
	v_cvt_pk_bf16_f32 v128, v128, v129
	v_exp_f32_e32 v130, v130
	s_waitcnt lgkmcnt(5)
	v_mfma_f32_32x32x16_bf16 v[80:95], v[152:155], v[192:195], v[80:95]
	v_exp_f32_e32 v131, v131
	v_add_f32_e32 v245, v245, v130
	v_add_f32_e32 v245, v245, v131
	v_cvt_pk_bf16_f32 v129, v130, v131
	v_mfma_f32_32x32x16_bf16 v[96:111], v[152:155], v[208:211], v[96:111]
	ds_read_b128 v[152:155], v242 offset:8192
	v_exp_f32_e32 v132, v132
	v_exp_f32_e32 v133, v133
	v_add_f32_e32 v245, v245, v132
	v_add_f32_e32 v245, v245, v133
	v_mfma_f32_32x32x16_bf16 v[48:63], v[112:115], v[168:171], v[48:63]
	v_cvt_pk_bf16_f32 v130, v132, v133
	v_exp_f32_e32 v134, v134
	v_exp_f32_e32 v135, v135
	v_add_f32_e32 v245, v245, v134
	s_waitcnt lgkmcnt(5)
	v_mfma_f32_32x32x16_bf16 v[80:95], v[156:159], v[196:199], v[80:95]
	v_add_f32_e32 v245, v245, v135
	v_cvt_pk_bf16_f32 v131, v134, v135
	v_exp_f32_e32 v120, v120
	v_exp_f32_e32 v121, v121
	v_mfma_f32_32x32x16_bf16 v[32:47], v[112:115], v[176:179], v[32:47]
	v_add_f32_e32 v244, v244, v120
	v_add_f32_e32 v244, v244, v121
	v_cvt_pk_bf16_f32 v120, v120, v121
	v_exp_f32_e32 v122, v122
	v_mfma_f32_32x32x16_bf16 v[96:111], v[156:159], v[212:215], v[96:111]
	ds_read_b128 v[156:159], v242 offset:9216
	v_exp_f32_e32 v123, v123
	v_add_f32_e32 v244, v244, v122
	v_add_f32_e32 v244, v244, v123
	v_cvt_pk_bf16_f32 v121, v122, v123
	s_waitcnt lgkmcnt(5)
	v_mfma_f32_32x32x16_bf16 v[80:95], v[160:163], v[216:219], v[80:95]
	v_exp_f32_e32 v124, v124
	v_exp_f32_e32 v125, v125
	v_add_f32_e32 v244, v244, v124
	v_add_f32_e32 v244, v244, v125
	v_mfma_f32_32x32x16_bf16 v[96:111], v[160:163], v[224:227], v[96:111]
	ds_read_b128 v[160:163], v242 offset:10240
	v_cvt_pk_bf16_f32 v122, v124, v125
	v_exp_f32_e32 v126, v126
	v_exp_f32_e32 v127, v127
	v_add_f32_e32 v244, v244, v126
	v_mfma_f32_32x32x16_bf16 v[16:31], v[128:131], v[168:171], v[16:31]
	v_add_f32_e32 v244, v244, v127
	v_cvt_pk_bf16_f32 v123, v126, v127
	v_exp_f32_e32 v136, v136
	v_exp_f32_e32 v137, v137
	s_waitcnt lgkmcnt(5)
	v_mfma_f32_32x32x16_bf16 v[80:95], v[164:167], v[220:223], v[80:95]
	v_add_f32_e32 v245, v245, v136
	v_add_f32_e32 v245, v245, v137
	v_cvt_pk_bf16_f32 v136, v136, v137
	v_exp_f32_e32 v138, v138
	v_mfma_f32_32x32x16_bf16 v[0:15], v[128:131], v[176:179], v[0:15]
	v_exp_f32_e32 v139, v139
	v_add_f32_e32 v245, v245, v138
	v_add_f32_e32 v245, v245, v139
	v_cvt_pk_bf16_f32 v137, v138, v139
	v_mfma_f32_32x32x16_bf16 v[96:111], v[164:167], v[228:231], v[96:111]
	ds_read_b128 v[164:167], v242 offset:11264
	v_exp_f32_e32 v140, v140
	v_exp_f32_e32 v141, v141
	v_add_f32_e32 v245, v245, v140
	v_add_f32_e32 v245, v245, v141
	v_mfma_f32_32x32x16_bf16 v[48:63], v[120:123], v[172:175], v[48:63]
	v_cvt_pk_bf16_f32 v138, v140, v141
	v_exp_f32_e32 v142, v142
	v_exp_f32_e32 v143, v143
	v_mfma_f32_32x32x16_bf16 v[32:47], v[120:123], v[180:183], v[32:47]
	v_add_f32_e32 v245, v245, v142
	v_add_f32_e32 v245, v245, v143
	v_cvt_pk_bf16_f32 v139, v142, v143
	ds_read_b64_tr_b16 v[168:169], v241 offset:49152
	ds_read_b64_tr_b16 v[170:171], v241 offset:50176
	ds_read_b64_tr_b16 v[176:177], v232 offset:49152
	ds_read_b64_tr_b16 v[178:179], v232 offset:50176
	v_mfma_f32_32x32x16_bf16 v[16:31], v[136:139], v[172:175], v[16:31]
	ds_read_b64_tr_b16 v[172:173], v241 offset:51200
	ds_read_b64_tr_b16 v[174:175], v241 offset:52224
	v_mfma_f32_32x32x16_bf16 v[0:15], v[136:139], v[180:183], v[0:15]
	ds_read_b64_tr_b16 v[180:181], v232 offset:51200
	ds_read_b64_tr_b16 v[182:183], v232 offset:52224
	s_branch .Lmla_tail
.Lmla_last:
	v_exp_f32_e32 v112, v112
	v_exp_f32_e32 v113, v113
	v_add_f32_e32 v244, v244, v112
	v_add_f32_e32 v244, v244, v113
	v_cvt_pk_bf16_f32 v112, v112, v113
	v_exp_f32_e32 v114, v114
	v_exp_f32_e32 v115, v115
	v_add_f32_e32 v244, v244, v114
	v_add_f32_e32 v244, v244, v115
	v_cvt_pk_bf16_f32 v113, v114, v115
	v_exp_f32_e32 v116, v116
	v_exp_f32_e32 v117, v117
	v_add_f32_e32 v244, v244, v116
	v_add_f32_e32 v244, v244, v117
	v_cvt_pk_bf16_f32 v114, v116, v117
	v_exp_f32_e32 v118, v118
	v_exp_f32_e32 v119, v119
	v_add_f32_e32 v244, v244, v118
	v_add_f32_e32 v244, v244, v119
	v_cvt_pk_bf16_f32 v115, v118, v119
	v_exp_f32_e32 v128, v128
	v_exp_f32_e32 v129, v129
	v_mfma_f32_32x32x16_bf16 v[48:63], v[112:115], v[168:171], v[48:63]
	v_add_f32_e32 v245, v245, v128
	v_add_f32_e32 v245, v245, v129
	v_cvt_pk_bf16_f32 v128, v128, v129
	v_exp_f32_e32 v130, v130
	v_exp_f32_e32 v131, v131
	v_add_f32_e32 v245, v245, v130
	v_add_f32_e32 v245, v245, v131
	v_cvt_pk_bf16_f32 v129, v130, v131
	v_exp_f32_e32 v132, v132
	v_exp_f32_e32 v133, v133
	v_mfma_f32_32x32x16_bf16 v[32:47], v[112:115], v[176:179], v[32:47]
	v_add_f32_e32 v245, v245, v132
	v_add_f32_e32 v245, v245, v133
	v_cvt_pk_bf16_f32 v130, v132, v133
	v_exp_f32_e32 v134, v134
	v_exp_f32_e32 v135, v135
	v_add_f32_e32 v245, v245, v134
	v_add_f32_e32 v245, v245, v135
	v_cvt_pk_bf16_f32 v131, v134, v135
	v_exp_f32_e32 v120, v120
	v_exp_f32_e32 v121, v121
	v_mfma_f32_32x32x16_bf16 v[16:31], v[128:131], v[168:171], v[16:31]
	v_add_f32_e32 v244, v244, v120
	v_add_f32_e32 v244, v244, v121
	v_cvt_pk_bf16_f32 v120, v120, v121
	v_exp_f32_e32 v122, v122
	v_exp_f32_e32 v123, v123
	v_add_f32_e32 v244, v244, v122
	v_add_f32_e32 v244, v244, v123
	v_cvt_pk_bf16_f32 v121, v122, v123
	v_exp_f32_e32 v124, v124
	v_exp_f32_e32 v125, v125
	v_mfma_f32_32x32x16_bf16 v[0:15], v[128:131], v[176:179], v[0:15]
	v_add_f32_e32 v244, v244, v124
	v_add_f32_e32 v244, v244, v125
	v_cvt_pk_bf16_f32 v122, v124, v125
	v_exp_f32_e32 v126, v126
	v_exp_f32_e32 v127, v127
	v_add_f32_e32 v244, v244, v126
	v_add_f32_e32 v244, v244, v127
	v_cvt_pk_bf16_f32 v123, v126, v127
	v_exp_f32_e32 v136, v136
	v_exp_f32_e32 v137, v137
	v_mfma_f32_32x32x16_bf16 v[48:63], v[120:123], v[172:175], v[48:63]
	v_add_f32_e32 v245, v245, v136
	v_add_f32_e32 v245, v245, v137
	v_cvt_pk_bf16_f32 v136, v136, v137
	v_exp_f32_e32 v138, v138
	v_exp_f32_e32 v139, v139
	v_add_f32_e32 v245, v245, v138
	v_add_f32_e32 v245, v245, v139
	v_cvt_pk_bf16_f32 v137, v138, v139
	v_exp_f32_e32 v140, v140
	v_mfma_f32_32x32x16_bf16 v[32:47], v[120:123], v[180:183], v[32:47]
	v_exp_f32_e32 v141, v141
	v_add_f32_e32 v245, v245, v140
	v_add_f32_e32 v245, v245, v141
	v_cvt_pk_bf16_f32 v138, v140, v141
	v_exp_f32_e32 v142, v142
	v_exp_f32_e32 v143, v143
	v_add_f32_e32 v245, v245, v142
	v_add_f32_e32 v245, v245, v143
	v_cvt_pk_bf16_f32 v139, v142, v143
	s_nop 1
	v_mfma_f32_32x32x16_bf16 v[16:31], v[136:139], v[172:175], v[16:31]
	v_mfma_f32_32x32x16_bf16 v[0:15], v[136:139], v[180:183], v[0:15]
.Lmla_tail:
	s_mov_b32 s12, 0x5f800000
	v_cmp_lt_f32_e32 vcc, s12, v244
	v_cmp_lt_f32_e64 s[52:53], s12, v245
	s_nop 1
	s_or_b64 vcc, vcc, s[52:53]
	s_cbranch_vccz .LBB0_483
	v_pk_mul_f32 v[244:245], v[244:245], s[92:93] op_sel_hi:[1,0]
	v_pk_mul_f32 v[62:63], v[62:63], s[92:93] op_sel_hi:[1,0]
	v_pk_mul_f32 v[60:61], v[60:61], s[92:93] op_sel_hi:[1,0]
	v_pk_mul_f32 v[58:59], v[58:59], s[92:93] op_sel_hi:[1,0]
	v_pk_mul_f32 v[56:57], v[56:57], s[92:93] op_sel_hi:[1,0]
	v_pk_mul_f32 v[54:55], v[54:55], s[92:93] op_sel_hi:[1,0]
	v_pk_mul_f32 v[52:53], v[52:53], s[92:93] op_sel_hi:[1,0]
	v_pk_mul_f32 v[50:51], v[50:51], s[92:93] op_sel_hi:[1,0]
	v_pk_mul_f32 v[48:49], v[48:49], s[92:93] op_sel_hi:[1,0]
	v_pk_mul_f32 v[46:47], v[46:47], s[92:93] op_sel_hi:[1,0]
	v_pk_mul_f32 v[44:45], v[44:45], s[92:93] op_sel_hi:[1,0]
	v_pk_mul_f32 v[42:43], v[42:43], s[92:93] op_sel_hi:[1,0]
	v_pk_mul_f32 v[40:41], v[40:41], s[92:93] op_sel_hi:[1,0]
	v_pk_mul_f32 v[38:39], v[38:39], s[92:93] op_sel_hi:[1,0]
	v_pk_mul_f32 v[36:37], v[36:37], s[92:93] op_sel_hi:[1,0]
	v_pk_mul_f32 v[34:35], v[34:35], s[92:93] op_sel_hi:[1,0]
	v_pk_mul_f32 v[32:33], v[32:33], s[92:93] op_sel_hi:[1,0]
	v_pk_mul_f32 v[30:31], v[30:31], s[92:93] op_sel_hi:[1,0]
	v_pk_mul_f32 v[28:29], v[28:29], s[92:93] op_sel_hi:[1,0]
	v_pk_mul_f32 v[26:27], v[26:27], s[92:93] op_sel_hi:[1,0]
	v_pk_mul_f32 v[24:25], v[24:25], s[92:93] op_sel_hi:[1,0]
	v_pk_mul_f32 v[22:23], v[22:23], s[92:93] op_sel_hi:[1,0]
	v_pk_mul_f32 v[20:21], v[20:21], s[92:93] op_sel_hi:[1,0]
	v_pk_mul_f32 v[18:19], v[18:19], s[92:93] op_sel_hi:[1,0]
	v_pk_mul_f32 v[16:17], v[16:17], s[92:93] op_sel_hi:[1,0]
	v_pk_mul_f32 v[14:15], v[14:15], s[92:93] op_sel_hi:[1,0]
	v_pk_mul_f32 v[12:13], v[12:13], s[92:93] op_sel_hi:[1,0]
	v_pk_mul_f32 v[10:11], v[10:11], s[92:93] op_sel_hi:[1,0]
	v_pk_mul_f32 v[8:9], v[8:9], s[92:93] op_sel_hi:[1,0]
	v_pk_mul_f32 v[6:7], v[6:7], s[92:93] op_sel_hi:[1,0]
	v_pk_mul_f32 v[4:5], v[4:5], s[92:93] op_sel_hi:[1,0]
	v_pk_mul_f32 v[2:3], v[2:3], s[92:93] op_sel_hi:[1,0]
	v_pk_mul_f32 v[0:1], v[0:1], s[92:93] op_sel_hi:[1,0]
	v_pk_add_f32 v[78:79], v[78:79], s[66:67] op_sel_hi:[1,0]
	v_pk_add_f32 v[76:77], v[76:77], s[66:67] op_sel_hi:[1,0]
	v_pk_add_f32 v[74:75], v[74:75], s[66:67] op_sel_hi:[1,0]
	v_pk_add_f32 v[72:73], v[72:73], s[66:67] op_sel_hi:[1,0]
	v_pk_add_f32 v[70:71], v[70:71], s[66:67] op_sel_hi:[1,0]
	v_pk_add_f32 v[68:69], v[68:69], s[66:67] op_sel_hi:[1,0]
	v_pk_add_f32 v[66:67], v[66:67], s[66:67] op_sel_hi:[1,0]
	v_pk_add_f32 v[64:65], v[64:65], s[66:67] op_sel_hi:[1,0]
	v_pk_add_f32 v[80:81], v[80:81], s[66:67] op_sel_hi:[1,0]
	v_pk_add_f32 v[82:83], v[82:83], s[66:67] op_sel_hi:[1,0]
	v_pk_add_f32 v[84:85], v[84:85], s[66:67] op_sel_hi:[1,0]
	v_pk_add_f32 v[86:87], v[86:87], s[66:67] op_sel_hi:[1,0]
	v_pk_add_f32 v[88:89], v[88:89], s[66:67] op_sel_hi:[1,0]
	v_pk_add_f32 v[90:91], v[90:91], s[66:67] op_sel_hi:[1,0]
	v_pk_add_f32 v[92:93], v[92:93], s[66:67] op_sel_hi:[1,0]
	v_pk_add_f32 v[94:95], v[94:95], s[66:67] op_sel_hi:[1,0]
	v_pk_add_f32 v[96:97], v[96:97], s[66:67] op_sel_hi:[1,0]
	v_pk_add_f32 v[98:99], v[98:99], s[66:67] op_sel_hi:[1,0]
	v_pk_add_f32 v[100:101], v[100:101], s[66:67] op_sel_hi:[1,0]
	v_pk_add_f32 v[102:103], v[102:103], s[66:67] op_sel_hi:[1,0]
	v_pk_add_f32 v[104:105], v[104:105], s[66:67] op_sel_hi:[1,0]
	v_pk_add_f32 v[106:107], v[106:107], s[66:67] op_sel_hi:[1,0]
	v_pk_add_f32 v[108:109], v[108:109], s[66:67] op_sel_hi:[1,0]
	v_pk_add_f32 v[110:111], v[110:111], s[66:67] op_sel_hi:[1,0]
.LBB0_483:
	s_add_u32 s26, s26, 0x20000
	s_addc_u32 s27, s27, 0
	s_add_u32 s22, s22, 0x20000
	s_addc_u32 s23, s23, 0
	s_add_u32 s18, s18, 0x2000
	s_addc_u32 s19, s19, 0
	s_add_u32 s24, s24, 0x20000
	s_addc_u32 s25, s25, 0
	s_add_u32 s16, s16, 0x2000
	s_addc_u32 s17, s17, 0
	s_add_u32 s20, s20, 0x20000
	s_addc_u32 s21, s21, 0
	s_add_u32 s14, s14, 0x2000
	s_addc_u32 s15, s15, 0
	s_cmp_eq_u32 s28, 64
	s_cbranch_scc1 .LBB0_490
	s_mov_b32 s29, s28
	s_add_i32 s28, s29, 1
	s_cmp_eq_u32 s29, 63
	s_cbranch_scc0 .LBB0_473
	s_branch .LBB0_481

.LBB0_490:
	v_mov_b32_e32 v152, v244
	v_mov_b32_e32 v153, v245
	s_lshl_b32 s2, s46, 2
	s_add_i32 s10, s2, 0
	s_add_i32 s10, s10, 0x1c800
	v_mov_b32_e32 v65, v152
	v_cmp_gt_u32_e64 s[2:3], 32, v234
	v_lshl_add_u32 v64, v253, 2, s10
	v_permlane32_swap_b32_e32 v152, v65
	s_and_saveexec_b64 s[8:9], s[2:3]
	s_cbranch_execz .LBB0_492
	v_add_f32_e32 v65, v152, v65
	v_div_scale_f32 v66, s[12:13], v65, v65, 1.0
	v_rcp_f32_e32 v67, v66
	v_div_scale_f32 v68, vcc, 1.0, v65, 1.0
	v_fma_f32 v69, -v66, v67, 1.0
	v_fmac_f32_e32 v67, v69, v67
	v_mul_f32_e32 v69, v68, v67
	v_fma_f32 v70, -v66, v69, v68
	v_fmac_f32_e32 v69, v70, v67
	v_fma_f32 v66, -v66, v69, v68
	v_div_fmas_f32 v66, v66, v67, v69
	v_div_fixup_f32 v65, v66, v65, 1.0
	ds_write_b32 v64, v65
